# v86 with the remaining non-temporal cache-output stores (pooling, sliding-window and memory K/V cache outputs) as default-policy stores
# baseline (speedup 1.0000x reference)
;     __device__ __forceinline__ void row_out(const f32x4 v0, const f32x4 v1, int row, int col, float& ss) const {
;         if (C) { float* rowp = C + (size_t)row * ldc + col; __builtin_nontemporal_store(v0, (f32x4*)rowp); __builtin_nontemporal_store(v1, (f32x4*)(rowp + 4)); }
;     __device__ __forceinline__ void operator()(const f32x4 (&acc)[2][2][4][2], const Unit& u, int wr, int wc, int fr, int fq) const {
;     ...
;                 for (int m = 0; m < 4; ++m) { const int row = row0 + ai * HALF + m * 16; float ss = 0.f;
;                     const float* rp = resP ? ((row < split ? resP + (size_t)row * ldc : resS + (size_t)(row - split) * ldc) + col0) : nullptr;
;                     f32x4 rv[2][2];
; #pragma unroll
;                     for (int bj = 0; bj < 2; ++bj) if (bj == 0 || !u.q) { rv[bj][0] = rp ? *(const f32x4*)(rp + bj * HALF) : (f32x4){0.f, 0.f, 0.f, 0.f}; rv[bj][1] = rp ? *(const f32x4*)(rp + bj * HALF + 4) : (f32x4){0.f, 0.f, 0.f, 0.f}; }
; #pragma unroll
;                     for (int bj = 0; bj < 2; ++bj) if (bj == 0 || !u.q) row_out(acc[ai][bj][m][0] + rv[bj][0], acc[ai][bj][m][1] + rv[bj][1], row, col0 + bj * HALF, ss);
;                     if (wxb) { ss += __shfl_xor(ss, 16); ss += __shfl_xor(ss, 32); if (fq == 0) unsafeAtomicAdd(SS + row, ss); } }
.LBB0_284:
	v_mov_b32_e32 v0, v113
	v_mov_b32_e32 v1, v112
	s_add_i32 s43, s43, s0
	s_lshl_b32 s18, s18, 7
	s_or_b32 s18, s18, s42
	v_add_u32_e32 v8, s43, v1
	v_ashrrev_i32_e32 v9, 31, v8
	v_lshl_add_u32 v10, v0, 3, s18
	v_lshlrev_b64 v[8:9], 12, v[8:9]
	v_ashrrev_i32_e32 v11, 31, v10
	v_lshl_add_u64 v[8:9], s[16:17], 0, v[8:9]
	v_lshl_add_u64 v[8:9], v[10:11], 2, v[8:9]
	v_pk_add_f32 v[2:3], v[74:75], 0 op_sel_hi:[1,0]
	v_pk_add_f32 v[0:1], v[72:73], 0 op_sel_hi:[1,0]
	v_add_co_u32_e32 v12, vcc, s39, v8
	v_pk_add_f32 v[6:7], v[94:95], 0 op_sel_hi:[1,0]
	v_pk_add_f32 v[4:5], v[92:93], 0 op_sel_hi:[1,0]
	global_store_dwordx4 v[8:9], v[0:3], off
	global_store_dwordx4 v[8:9], v[4:7], off offset:16
	v_addc_co_u32_e32 v13, vcc, 0, v9, vcc
	v_pk_add_f32 v[2:3], v[78:79], 0 op_sel_hi:[1,0]
	v_pk_add_f32 v[0:1], v[76:77], 0 op_sel_hi:[1,0]
	v_pk_add_f32 v[6:7], v[82:83], 0 op_sel_hi:[1,0]
	v_pk_add_f32 v[4:5], v[80:81], 0 op_sel_hi:[1,0]
	v_lshl_add_u64 v[10:11], v[8:9], 0, s[10:11]
	global_store_dwordx4 v[12:13], v[0:3], off
	global_store_dwordx4 v[10:11], v[4:7], off offset:16
	v_add_co_u32_e32 v12, vcc, s40, v8
	v_pk_add_f32 v[2:3], v[66:67], 0 op_sel_hi:[1,0]
	v_pk_add_f32 v[0:1], v[64:65], 0 op_sel_hi:[1,0]
	v_lshl_add_u64 v[10:11], v[8:9], 0, s[12:13]
	v_addc_co_u32_e32 v13, vcc, 0, v9, vcc
	v_readlane_b32 s18, v240, 1
	v_pk_add_f32 v[6:7], v[70:71], 0 op_sel_hi:[1,0]
	v_pk_add_f32 v[4:5], v[68:69], 0 op_sel_hi:[1,0]
	global_store_dwordx4 v[12:13], v[0:3], off
	global_store_dwordx4 v[10:11], v[4:7], off offset:16
	v_lshl_add_u64 v[10:11], v[8:9], 0, s[14:15]
	v_add_co_u32_e32 v8, vcc, 0x30000, v8
	s_add_i32 s41, s41, s18
	v_pk_add_f32 v[2:3], v[86:87], 0 op_sel_hi:[1,0]
	v_pk_add_f32 v[0:1], v[84:85], 0 op_sel_hi:[1,0]
	v_addc_co_u32_e32 v9, vcc, 0, v9, vcc
	s_cmp_lt_i32 s41, 64
	v_pk_add_f32 v[6:7], v[90:91], 0 op_sel_hi:[1,0]
	v_pk_add_f32 v[4:5], v[88:89], 0 op_sel_hi:[1,0]
	global_store_dwordx4 v[8:9], v[0:3], off
	global_store_dwordx4 v[10:11], v[4:7], off offset:16
	s_barrier
	v_readlane_b32 s19, v240, 2
	s_cbranch_scc0 .LBB0_281

; #define LAS __attribute__((address_space(3)))
; __device__ __forceinline__ bf16x8 pack8(const float (&o)[8]) { v4u w; w.x = pk2(o[0], o[1]); w.y = pk2(o[2], o[3]); w.z = pk2(o[4], o[5]); w.w = pk2(o[6], o[7]); return __builtin_bit_cast(bf16x8, w); }
; template <bool SAMPLE>
; __device__ __forceinline__ void swa_unit(const Params& p, LAS unsigned char* lds, int unit, int tid, int wave, int lane) {
;     ...
;             *(LAS bf16x8*)(Kl + s * SWA_KS + sub * 8) = pack8(k);
;             *(LAS bf16x8*)(Vt + s * SWA_VS + sub * 8) = pack8(v);
;             if (!SAMPLE) { if (nb == 63 && s >= 128) { const size_t o = (((size_t)b * 128 + (s - 128)) * 4 + kvh) * 64 + sub * 8;
;                     *(f32x4*)(p.out + O_SKP + o) = (f32x4){k[0], k[1], k[2], k[3]}; *(f32x4*)(p.out + O_SKP + o + 4) = (f32x4){k[4], k[5], k[6], k[7]};
;                     *(f32x4*)(p.out + O_SVP + o) = (f32x4){v[0], v[1], v[2], v[3]}; *(f32x4*)(p.out + O_SVP + o + 4) = (f32x4){v[4], v[5], v[6], v[7]}; } }
;             else { if (s >= 8 && s < 136) { const size_t o = (((size_t)b * 128 + (s - 8)) * 4 + kvh) * 64 + sub * 8;
;                     __builtin_nontemporal_store((f32x4){k[0], k[1], k[2], k[3]}, (f32x4*)(p.out + O_SKS + o)); __builtin_nontemporal_store((f32x4){k[4], k[5], k[6], k[7]}, (f32x4*)(p.out + O_SKS + o + 4));
;                     __builtin_nontemporal_store((f32x4){v[0], v[1], v[2], v[3]}, (f32x4*)(p.out + O_SVS + o)); __builtin_nontemporal_store((f32x4){v[4], v[5], v[6], v[7]}, (f32x4*)(p.out + O_SVS + o + 4)); } }
.LBB0_1368:
	s_or_b64 exec, exec, s[20:21]
	v_readlane_b32 s12, v239, 40
	v_readlane_b32 s13, v239, 41
	s_waitcnt vmcnt(2)
	v_cvt_pk_bf16_f32 v42, v102, v103
	s_waitcnt lgkmcnt(0)
	v_cvt_pk_bf16_f32 v43, v104, v105
	v_cvt_pk_bf16_f32 v44, v98, v99
	v_cvt_pk_bf16_f32 v45, v100, v101
	ds_write_b128 v175, v[42:45]
	s_waitcnt vmcnt(1)
	v_cvt_pk_bf16_f32 v0, v0, v1
	v_cvt_pk_bf16_f32 v1, v2, v3
	s_waitcnt vmcnt(0)
	v_cvt_pk_bf16_f32 v2, v4, v5
	v_cvt_pk_bf16_f32 v3, v6, v7
	ds_write_b128 v175, v[0:3] offset:36864
	s_and_b64 exec, exec, s[12:13]
	s_cbranch_execz .LBB0_1370
	v_mov_b32_e32 v1, s1
	v_or_b32_e32 v0, s0, v196
	v_lshlrev_b64 v[0:1], 8, v[0:1]
	v_lshl_or_b32 v0, v194, 2, v0
	v_lshl_add_u64 v[2:3], s[58:59], 0, v[0:1]
	global_store_dwordx4 v[2:3], v[102:105], off
	v_lshl_add_u64 v[2:3], s[92:93], 0, v[0:1]
	s_mov_b32 s12, 0x8ade000
	v_add_co_u32_e32 v4, vcc, s12, v2
	v_lshl_add_u64 v[0:1], s[60:61], 0, v[0:1]
	s_nop 0
	v_addc_co_u32_e32 v5, vcc, 0, v3, vcc
	global_store_dwordx4 v[0:1], v[18:21], off
	v_add_co_u32_e32 v0, vcc, 0x9ade000, v2
	global_store_dwordx4 v[4:5], v[98:101], off offset:16
	s_nop 0
	v_addc_co_u32_e32 v1, vcc, 0, v3, vcc
	global_store_dwordx4 v[0:1], v[22:25], off offset:16

; #define LAS __attribute__((address_space(3)))
; __device__ __forceinline__ bf16x8 pack8(const float (&o)[8]) { v4u w; w.x = pk2(o[0], o[1]); w.y = pk2(o[2], o[3]); w.z = pk2(o[4], o[5]); w.w = pk2(o[6], o[7]); return __builtin_bit_cast(bf16x8, w); }
; template <bool SAMPLE>
; __device__ __forceinline__ void swa_unit(const Params& p, LAS unsigned char* lds, int unit, int tid, int wave, int lane) {
;     ...
;             *(LAS bf16x8*)(Kl + s * SWA_KS + sub * 8) = pack8(k);
;             *(LAS bf16x8*)(Vt + s * SWA_VS + sub * 8) = pack8(v);
;             if (!SAMPLE) { if (nb == 63 && s >= 128) { const size_t o = (((size_t)b * 128 + (s - 128)) * 4 + kvh) * 64 + sub * 8;
;                     *(f32x4*)(p.out + O_SKP + o) = (f32x4){k[0], k[1], k[2], k[3]}; *(f32x4*)(p.out + O_SKP + o + 4) = (f32x4){k[4], k[5], k[6], k[7]};
;                     *(f32x4*)(p.out + O_SVP + o) = (f32x4){v[0], v[1], v[2], v[3]}; *(f32x4*)(p.out + O_SVP + o + 4) = (f32x4){v[4], v[5], v[6], v[7]}; } }
;             else { if (s >= 8 && s < 136) { const size_t o = (((size_t)b * 128 + (s - 8)) * 4 + kvh) * 64 + sub * 8;
;                     __builtin_nontemporal_store((f32x4){k[0], k[1], k[2], k[3]}, (f32x4*)(p.out + O_SKS + o)); __builtin_nontemporal_store((f32x4){k[4], k[5], k[6], k[7]}, (f32x4*)(p.out + O_SKS + o + 4));
;                     __builtin_nontemporal_store((f32x4){v[0], v[1], v[2], v[3]}, (f32x4*)(p.out + O_SVS + o)); __builtin_nontemporal_store((f32x4){v[4], v[5], v[6], v[7]}, (f32x4*)(p.out + O_SVS + o + 4)); } }
.LBB0_1421:
	s_or_b64 exec, exec, s[20:21]
	v_readlane_b32 s12, v239, 46
	v_cvt_pk_bf16_f32 v0, v94, v95
	s_waitcnt lgkmcnt(0)
	v_cvt_pk_bf16_f32 v1, v96, v97
	v_cvt_pk_bf16_f32 v2, v90, v91
	v_cvt_pk_bf16_f32 v3, v92, v93
	v_readlane_b32 s13, v239, 47
	ds_write_b128 v175, v[0:3] offset:9216
	v_cvt_pk_bf16_f32 v0, v8, v9
	v_cvt_pk_bf16_f32 v1, v10, v11
	v_cvt_pk_bf16_f32 v2, v12, v13
	v_cvt_pk_bf16_f32 v3, v14, v15
	ds_write_b128 v175, v[0:3] offset:46080
	s_and_b64 exec, exec, s[12:13]
	s_cbranch_execz .LBB0_1423
	v_mov_b32_e32 v1, s1
	v_or_b32_e32 v0, s0, v198
	v_lshlrev_b64 v[0:1], 8, v[0:1]
	v_lshl_or_b32 v0, v194, 2, v0
	v_lshl_add_u64 v[2:3], s[58:59], 0, v[0:1]
	global_store_dwordx4 v[2:3], v[94:97], off
	v_lshl_add_u64 v[2:3], s[92:93], 0, v[0:1]
	s_mov_b32 s12, 0x8ade000
	v_add_co_u32_e32 v4, vcc, s12, v2
	v_lshl_add_u64 v[0:1], s[60:61], 0, v[0:1]
	s_nop 0
	v_addc_co_u32_e32 v5, vcc, 0, v3, vcc
	global_store_dwordx4 v[0:1], v[26:29], off
	v_add_co_u32_e32 v0, vcc, 0x9ade000, v2
	global_store_dwordx4 v[4:5], v[90:93], off offset:16
	s_nop 0
	v_addc_co_u32_e32 v1, vcc, 0, v3, vcc
	global_store_dwordx4 v[0:1], v[30:33], off offset:16

; #define LAS __attribute__((address_space(3)))
; __device__ __forceinline__ bf16x8 pack8(const float (&o)[8]) { v4u w; w.x = pk2(o[0], o[1]); w.y = pk2(o[2], o[3]); w.z = pk2(o[4], o[5]); w.w = pk2(o[6], o[7]); return __builtin_bit_cast(bf16x8, w); }
; template <bool SAMPLE>
; __device__ __forceinline__ void swa_unit(const Params& p, LAS unsigned char* lds, int unit, int tid, int wave, int lane) {
;     ...
;             *(LAS bf16x8*)(Kl + s * SWA_KS + sub * 8) = pack8(k);
;             *(LAS bf16x8*)(Vt + s * SWA_VS + sub * 8) = pack8(v);
;             if (!SAMPLE) { if (nb == 63 && s >= 128) { const size_t o = (((size_t)b * 128 + (s - 128)) * 4 + kvh) * 64 + sub * 8;
;                     *(f32x4*)(p.out + O_SKP + o) = (f32x4){k[0], k[1], k[2], k[3]}; *(f32x4*)(p.out + O_SKP + o + 4) = (f32x4){k[4], k[5], k[6], k[7]};
;                     *(f32x4*)(p.out + O_SVP + o) = (f32x4){v[0], v[1], v[2], v[3]}; *(f32x4*)(p.out + O_SVP + o + 4) = (f32x4){v[4], v[5], v[6], v[7]}; } }
;             else { if (s >= 8 && s < 136) { const size_t o = (((size_t)b * 128 + (s - 8)) * 4 + kvh) * 64 + sub * 8;
;                     __builtin_nontemporal_store((f32x4){k[0], k[1], k[2], k[3]}, (f32x4*)(p.out + O_SKS + o)); __builtin_nontemporal_store((f32x4){k[4], k[5], k[6], k[7]}, (f32x4*)(p.out + O_SKS + o + 4));
;                     __builtin_nontemporal_store((f32x4){v[0], v[1], v[2], v[3]}, (f32x4*)(p.out + O_SVS + o)); __builtin_nontemporal_store((f32x4){v[4], v[5], v[6], v[7]}, (f32x4*)(p.out + O_SVS + o + 4)); } }
.LBB0_1474:
	s_or_b64 exec, exec, s[20:21]
	v_readlane_b32 s12, v239, 50
	v_cvt_pk_bf16_f32 v0, v78, v79
	s_waitcnt lgkmcnt(0)
	v_cvt_pk_bf16_f32 v1, v80, v81
	v_cvt_pk_bf16_f32 v2, v74, v75
	v_cvt_pk_bf16_f32 v3, v76, v77
	v_readlane_b32 s13, v239, 51
	ds_write_b128 v175, v[0:3] offset:18432
	v_cvt_pk_bf16_f32 v0, v66, v67
	v_cvt_pk_bf16_f32 v1, v68, v69
	v_cvt_pk_bf16_f32 v2, v70, v71
	v_cvt_pk_bf16_f32 v3, v72, v73
	ds_write_b128 v175, v[0:3] offset:55296
	s_and_b64 exec, exec, s[12:13]
	s_cbranch_execz .LBB0_1476
	v_mov_b32_e32 v1, s1
	v_or_b32_e32 v0, s0, v200
	v_lshlrev_b64 v[0:1], 8, v[0:1]
	v_lshl_or_b32 v0, v194, 2, v0
	v_lshl_add_u64 v[2:3], s[58:59], 0, v[0:1]
	global_store_dwordx4 v[2:3], v[78:81], off
	v_lshl_add_u64 v[2:3], s[92:93], 0, v[0:1]
	s_mov_b32 s0, 0x8ade000
	v_add_co_u32_e32 v4, vcc, s0, v2
	v_lshl_add_u64 v[0:1], s[60:61], 0, v[0:1]
	s_nop 0
	v_addc_co_u32_e32 v5, vcc, 0, v3, vcc
	global_store_dwordx4 v[0:1], v[34:37], off
	v_add_co_u32_e32 v0, vcc, 0x9ade000, v2
	global_store_dwordx4 v[4:5], v[74:77], off offset:16
	s_nop 0
	v_addc_co_u32_e32 v1, vcc, 0, v3, vcc
	global_store_dwordx4 v[0:1], v[38:41], off offset:16

; #define LAS __attribute__((address_space(3)))
; __device__ __forceinline__ bf16x8 pack8(const float (&o)[8]) { v4u w; w.x = pk2(o[0], o[1]); w.y = pk2(o[2], o[3]); w.z = pk2(o[4], o[5]); w.w = pk2(o[6], o[7]); return __builtin_bit_cast(bf16x8, w); }
; template <bool SAMPLE>
; __device__ __forceinline__ void swa_unit(const Params& p, LAS unsigned char* lds, int unit, int tid, int wave, int lane) {
;     ...
;             *(LAS bf16x8*)(Kl + s * SWA_KS + sub * 8) = pack8(k);
;             *(LAS bf16x8*)(Vt + s * SWA_VS + sub * 8) = pack8(v);
;             if (!SAMPLE) { if (nb == 63 && s >= 128) { const size_t o = (((size_t)b * 128 + (s - 128)) * 4 + kvh) * 64 + sub * 8;
;                     *(f32x4*)(p.out + O_SKP + o) = (f32x4){k[0], k[1], k[2], k[3]}; *(f32x4*)(p.out + O_SKP + o + 4) = (f32x4){k[4], k[5], k[6], k[7]};
;                     *(f32x4*)(p.out + O_SVP + o) = (f32x4){v[0], v[1], v[2], v[3]}; *(f32x4*)(p.out + O_SVP + o + 4) = (f32x4){v[4], v[5], v[6], v[7]}; } }
;             else { if (s >= 8 && s < 136) { const size_t o = (((size_t)b * 128 + (s - 8)) * 4 + kvh) * 64 + sub * 8;
;                     __builtin_nontemporal_store((f32x4){k[0], k[1], k[2], k[3]}, (f32x4*)(p.out + O_SKS + o)); __builtin_nontemporal_store((f32x4){k[4], k[5], k[6], k[7]}, (f32x4*)(p.out + O_SKS + o + 4));
;                     __builtin_nontemporal_store((f32x4){v[0], v[1], v[2], v[3]}, (f32x4*)(p.out + O_SVS + o)); __builtin_nontemporal_store((f32x4){v[4], v[5], v[6], v[7]}, (f32x4*)(p.out + O_SVS + o + 4)); } }
.LBB0_2249:
	s_or_b64 exec, exec, s[38:39]
	s_waitcnt vmcnt(2)
	v_cvt_pk_bf16_f32 v42, v102, v103
	s_waitcnt lgkmcnt(0)
	v_cvt_pk_bf16_f32 v43, v104, v105
	v_cvt_pk_bf16_f32 v44, v98, v99
	v_cvt_pk_bf16_f32 v45, v100, v101
	ds_write_b128 v160, v[42:45]
	s_waitcnt vmcnt(1)
	v_cvt_pk_bf16_f32 v0, v0, v1
	v_cvt_pk_bf16_f32 v1, v2, v3
	s_waitcnt vmcnt(0)
	v_cvt_pk_bf16_f32 v2, v4, v5
	v_cvt_pk_bf16_f32 v3, v6, v7
	ds_write_b128 v160, v[0:3] offset:36864
	s_and_b64 exec, exec, s[56:57]
	s_cbranch_execz .LBB0_2251
	v_mov_b32_e32 v1, s3
	v_or_b32_e32 v0, s2, v196
	v_lshlrev_b64 v[0:1], 8, v[0:1]
	v_lshl_or_b32 v0, v194, 2, v0
	v_lshl_add_u64 v[2:3], s[24:25], 0, v[0:1]
	global_store_dwordx4 v[2:3], v[102:105], off
	v_lshl_add_u64 v[2:3], s[92:93], 0, v[0:1]
	v_add_co_u32_e32 v4, vcc, s7, v2
	v_lshl_add_u64 v[0:1], s[28:29], 0, v[0:1]
	s_nop 0
	v_addc_co_u32_e32 v5, vcc, 0, v3, vcc
	global_store_dwordx4 v[0:1], v[18:21], off
	v_add_co_u32_e32 v0, vcc, 0x9ade000, v2
	global_store_dwordx4 v[4:5], v[98:101], off offset:16
	s_nop 0
	v_addc_co_u32_e32 v1, vcc, 0, v3, vcc
	global_store_dwordx4 v[0:1], v[22:25], off offset:16

; #define LAS __attribute__((address_space(3)))
; __device__ __forceinline__ bf16x8 pack8(const float (&o)[8]) { v4u w; w.x = pk2(o[0], o[1]); w.y = pk2(o[2], o[3]); w.z = pk2(o[4], o[5]); w.w = pk2(o[6], o[7]); return __builtin_bit_cast(bf16x8, w); }
; template <bool SAMPLE>
; __device__ __forceinline__ void swa_unit(const Params& p, LAS unsigned char* lds, int unit, int tid, int wave, int lane) {
;     ...
;             *(LAS bf16x8*)(Kl + s * SWA_KS + sub * 8) = pack8(k);
;             *(LAS bf16x8*)(Vt + s * SWA_VS + sub * 8) = pack8(v);
;             if (!SAMPLE) { if (nb == 63 && s >= 128) { const size_t o = (((size_t)b * 128 + (s - 128)) * 4 + kvh) * 64 + sub * 8;
;                     *(f32x4*)(p.out + O_SKP + o) = (f32x4){k[0], k[1], k[2], k[3]}; *(f32x4*)(p.out + O_SKP + o + 4) = (f32x4){k[4], k[5], k[6], k[7]};
;                     *(f32x4*)(p.out + O_SVP + o) = (f32x4){v[0], v[1], v[2], v[3]}; *(f32x4*)(p.out + O_SVP + o + 4) = (f32x4){v[4], v[5], v[6], v[7]}; } }
;             else { if (s >= 8 && s < 136) { const size_t o = (((size_t)b * 128 + (s - 8)) * 4 + kvh) * 64 + sub * 8;
;                     __builtin_nontemporal_store((f32x4){k[0], k[1], k[2], k[3]}, (f32x4*)(p.out + O_SKS + o)); __builtin_nontemporal_store((f32x4){k[4], k[5], k[6], k[7]}, (f32x4*)(p.out + O_SKS + o + 4));
;                     __builtin_nontemporal_store((f32x4){v[0], v[1], v[2], v[3]}, (f32x4*)(p.out + O_SVS + o)); __builtin_nontemporal_store((f32x4){v[4], v[5], v[6], v[7]}, (f32x4*)(p.out + O_SVS + o + 4)); } }
.LBB0_2302:
	s_or_b64 exec, exec, s[38:39]
	v_cvt_pk_bf16_f32 v0, v94, v95
	s_waitcnt lgkmcnt(0)
	v_cvt_pk_bf16_f32 v1, v96, v97
	v_cvt_pk_bf16_f32 v2, v90, v91
	v_cvt_pk_bf16_f32 v3, v92, v93
	ds_write_b128 v160, v[0:3] offset:9216
	v_cvt_pk_bf16_f32 v0, v8, v9
	v_cvt_pk_bf16_f32 v1, v10, v11
	v_cvt_pk_bf16_f32 v2, v12, v13
	v_cvt_pk_bf16_f32 v3, v14, v15
	ds_write_b128 v160, v[0:3] offset:46080
	s_and_b64 exec, exec, s[84:85]
	s_cbranch_execz .LBB0_2304
	v_mov_b32_e32 v1, s3
	v_or_b32_e32 v0, s2, v198
	v_lshlrev_b64 v[0:1], 8, v[0:1]
	v_lshl_or_b32 v0, v194, 2, v0
	v_lshl_add_u64 v[2:3], s[24:25], 0, v[0:1]
	global_store_dwordx4 v[2:3], v[94:97], off
	v_lshl_add_u64 v[2:3], s[92:93], 0, v[0:1]
	v_add_co_u32_e32 v4, vcc, s7, v2
	v_lshl_add_u64 v[0:1], s[28:29], 0, v[0:1]
	s_nop 0
	v_addc_co_u32_e32 v5, vcc, 0, v3, vcc
	global_store_dwordx4 v[0:1], v[26:29], off
	v_add_co_u32_e32 v0, vcc, 0x9ade000, v2
	global_store_dwordx4 v[4:5], v[90:93], off offset:16
	s_nop 0
	v_addc_co_u32_e32 v1, vcc, 0, v3, vcc
	global_store_dwordx4 v[0:1], v[30:33], off offset:16

; #define LAS __attribute__((address_space(3)))
; __device__ __forceinline__ bf16x8 pack8(const float (&o)[8]) { v4u w; w.x = pk2(o[0], o[1]); w.y = pk2(o[2], o[3]); w.z = pk2(o[4], o[5]); w.w = pk2(o[6], o[7]); return __builtin_bit_cast(bf16x8, w); }
; template <bool SAMPLE>
; __device__ __forceinline__ void swa_unit(const Params& p, LAS unsigned char* lds, int unit, int tid, int wave, int lane) {
;     ...
;             *(LAS bf16x8*)(Kl + s * SWA_KS + sub * 8) = pack8(k);
;             *(LAS bf16x8*)(Vt + s * SWA_VS + sub * 8) = pack8(v);
;             if (!SAMPLE) { if (nb == 63 && s >= 128) { const size_t o = (((size_t)b * 128 + (s - 128)) * 4 + kvh) * 64 + sub * 8;
;                     *(f32x4*)(p.out + O_SKP + o) = (f32x4){k[0], k[1], k[2], k[3]}; *(f32x4*)(p.out + O_SKP + o + 4) = (f32x4){k[4], k[5], k[6], k[7]};
;                     *(f32x4*)(p.out + O_SVP + o) = (f32x4){v[0], v[1], v[2], v[3]}; *(f32x4*)(p.out + O_SVP + o + 4) = (f32x4){v[4], v[5], v[6], v[7]}; } }
;             else { if (s >= 8 && s < 136) { const size_t o = (((size_t)b * 128 + (s - 8)) * 4 + kvh) * 64 + sub * 8;
;                     __builtin_nontemporal_store((f32x4){k[0], k[1], k[2], k[3]}, (f32x4*)(p.out + O_SKS + o)); __builtin_nontemporal_store((f32x4){k[4], k[5], k[6], k[7]}, (f32x4*)(p.out + O_SKS + o + 4));
;                     __builtin_nontemporal_store((f32x4){v[0], v[1], v[2], v[3]}, (f32x4*)(p.out + O_SVS + o)); __builtin_nontemporal_store((f32x4){v[4], v[5], v[6], v[7]}, (f32x4*)(p.out + O_SVS + o + 4)); } }
.LBB0_2355:
	s_or_b64 exec, exec, s[38:39]
	v_readlane_b32 s12, v239, 50
	v_cvt_pk_bf16_f32 v0, v78, v79
	s_waitcnt lgkmcnt(0)
	v_cvt_pk_bf16_f32 v1, v80, v81
	v_cvt_pk_bf16_f32 v2, v74, v75
	v_cvt_pk_bf16_f32 v3, v76, v77
	v_readlane_b32 s13, v239, 51
	ds_write_b128 v160, v[0:3] offset:18432
	v_cvt_pk_bf16_f32 v0, v66, v67
	v_cvt_pk_bf16_f32 v1, v68, v69
	v_cvt_pk_bf16_f32 v2, v70, v71
	v_cvt_pk_bf16_f32 v3, v72, v73
	ds_write_b128 v160, v[0:3] offset:55296
	s_and_b64 exec, exec, s[12:13]
	s_cbranch_execz .LBB0_2357
	v_mov_b32_e32 v1, s3
	v_or_b32_e32 v0, s2, v200
	v_lshlrev_b64 v[0:1], 8, v[0:1]
	v_lshl_or_b32 v0, v194, 2, v0
	v_lshl_add_u64 v[2:3], s[24:25], 0, v[0:1]
	global_store_dwordx4 v[2:3], v[78:81], off
	v_lshl_add_u64 v[2:3], s[92:93], 0, v[0:1]
	v_add_co_u32_e32 v4, vcc, s7, v2
	v_lshl_add_u64 v[0:1], s[28:29], 0, v[0:1]
	s_nop 0
	v_addc_co_u32_e32 v5, vcc, 0, v3, vcc
	global_store_dwordx4 v[0:1], v[34:37], off
	v_add_co_u32_e32 v0, vcc, 0x9ade000, v2
	global_store_dwordx4 v[4:5], v[74:77], off offset:16
	s_nop 0
	v_addc_co_u32_e32 v1, vcc, 0, v3, vcc
	global_store_dwordx4 v[0:1], v[38:41], off offset:16
